# scan compute loop: VOP2 encodings for the state-scaling multiplies and two idle slots between MFMAs removed
# baseline (speedup 1.0000x reference)
; #define LAS __attribute__((address_space(3)))
; #define PACK8(v, base) pack8f((v)[(base) + 0], (v)[(base) + 1], (v)[(base) + 2], (v)[(base) + 3], (v)[(base) + 4], (v)[(base) + 5], (v)[(base) + 6], (v)[(base) + 7])
; #define SBAR() __builtin_amdgcn_sched_barrier(0)
; #define LOAD_WQ(f, g) do { _Pragma("unroll") for (int e = 0; e < 2; ++e) { f[4 * e] = LDF((2 * (g) + e) * 1024); f[4 * e + 1] = LDF((8 + 2 * (g) + e) * 1024); \
;                 f[4 * e + 2] = LDF(16384 + (2 * (g) + e) * 1024); f[4 * e + 3] = LDF(16384 + (8 + 2 * (g) + e) * 1024); } } while (0)
; #define COMP_WQ(f, g) do { _Pragma("unroll") for (int e = 0; e < 2; ++e) { const bf16x8 sb = PACK8(S[(2 * (g) + e) >> 1], ((2 * (g) + e) & 1) * 8); \
;                 vn[0] = MFMA32(f[4 * e], sb, vn[0]); vn[1] = MFMA32(f[4 * e + 1], sb, vn[1]); o[0] = MFMA32(f[4 * e + 2], sb, o[0]); o[1] = MFMA32(f[4 * e + 3], sb, o[1]); } } while (0)
; DI void gdn_scan(const Args& a, int l, int bh, LAS unsigned char* lds, const int tidx, const bool nostore) {
;     ...
;             const LAS unsigned char* buf = lds + (n & 1) * REC_BYTES + lane * 16;
;             bf16x8 fa[8], fb[8];
;     ...
;             LOAD_WQ(fa, 0); SBAR(); LOAD_WQ(fb, 1); SBAR();
;             COMP_WQ(fa, 0); SBAR(); LOAD_WQ(fa, 2); SBAR();
;             COMP_WQ(fb, 1); SBAR(); LOAD_WQ(fb, 3); SBAR();
;             COMP_WQ(fa, 2); SBAR();
; #pragma unroll
;             for (int e = 0; e < 8; ++e) fa[e] = LDF(49152 + e * 1024);
;             SBAR();
;             COMP_WQ(fb, 3); SBAR();
; #pragma unroll
;             for (int e = 0; e < 8; ++e) fb[e] = LDF(32768 + e * 1024);
;             SBAR();
;             bf16x8 Vb[4];
; #pragma unroll
;             for (int s2 = 0; s2 < 4; ++s2) Vb[s2] = PACK8(vn[s2 >> 1], (s2 & 1) * 8);
.Lscan_top_done:
	s_and_b32 s5, s4, 1
	s_mul_i32 s6, s5, 0xe000
	v_add_u32_e32 v204, s6, v150
	ds_read_b128 v[152:155], v204
	ds_read_b128 v[156:159], v204 offset:8192
	ds_read_b128 v[64:67], v204 offset:16384
	ds_read_b128 v[68:71], v204 offset:24576
	ds_read_b128 v[160:163], v204 offset:1024
	ds_read_b128 v[164:167], v204 offset:9216
	ds_read_b128 v[168:171], v204 offset:17408
	ds_read_b128 v[172:175], v204 offset:25600
	ds_read_b128 v[176:179], v204 offset:2048
	ds_read_b128 v[180:183], v204 offset:3072
	ds_read_b128 v[184:187], v204 offset:10240
	ds_read_b128 v[188:191], v204 offset:11264
	ds_read_b128 v[192:195], v204 offset:18432
	ds_read_b128 v[196:199], v204 offset:19456
	ds_read_b128 v[200:203], v204 offset:26624
	ds_read_b128 v[222:225], v204 offset:27648
	v_cvt_pk_bf16_f32 v226, v48, v49
	v_cvt_pk_bf16_f32 v227, v50, v51
	v_cvt_pk_bf16_f32 v228, v52, v53
	v_cvt_pk_bf16_f32 v229, v54, v55
	v_cvt_pk_bf16_f32 v230, v56, v57
	v_cvt_pk_bf16_f32 v231, v58, v59
	s_waitcnt lgkmcnt(13)
	v_mfma_f32_32x32x16_bf16 v[80:95], v[64:67], v[226:229], 0
	v_cvt_pk_bf16_f32 v232, v60, v61
	v_cvt_pk_bf16_f32 v233, v62, v63
	s_waitcnt lgkmcnt(12)
	v_mfma_f32_32x32x16_bf16 v[64:79], v[68:71], v[226:229], 0
	s_waitcnt lgkmcnt(9)
	v_mfma_f32_32x32x16_bf16 v[80:95], v[168:171], v[230:233], v[80:95]
	s_waitcnt lgkmcnt(8)
	v_mfma_f32_32x32x16_bf16 v[64:79], v[172:175], v[230:233], v[64:79]
	v_mfma_f32_32x32x16_bf16 v[112:127], v[152:155], v[226:229], v[112:127]
	v_mfma_f32_32x32x16_bf16 v[96:111], v[156:159], v[226:229], v[96:111]
	v_mfma_f32_32x32x16_bf16 v[112:127], v[160:163], v[230:233], v[112:127]
	ds_read_b128 v[152:155], v204 offset:4096
	ds_read_b128 v[156:159], v204 offset:5120
	ds_read_b128 v[160:163], v204 offset:12288
	ds_read_b128 v[168:171], v204 offset:13312
	ds_read_b128 v[172:175], v204 offset:20480
	ds_read_b128 v[226:229], v204 offset:21504
	ds_read_b128 v[234:237], v204 offset:28672
	ds_read_b128 v[248:251], v204 offset:29696
	v_mfma_f32_32x32x16_bf16 v[96:111], v[164:167], v[230:233], v[96:111]
	v_cvt_pk_bf16_f32 v164, v32, v33
	v_cvt_pk_bf16_f32 v165, v34, v35
	v_cvt_pk_bf16_f32 v166, v36, v37
	v_cvt_pk_bf16_f32 v167, v38, v39
	s_waitcnt lgkmcnt(11)
	s_nop 0
	v_mfma_f32_32x32x16_bf16 v[80:95], v[192:195], v[164:167], v[80:95]
	v_cvt_pk_bf16_f32 v192, v40, v41
	v_cvt_pk_bf16_f32 v193, v42, v43
	v_cvt_pk_bf16_f32 v194, v44, v45
	v_cvt_pk_bf16_f32 v195, v46, v47
	s_waitcnt lgkmcnt(9)
	v_mfma_f32_32x32x16_bf16 v[64:79], v[200:203], v[164:167], v[64:79]
	v_mfma_f32_32x32x16_bf16 v[80:95], v[196:199], v[192:195], v[80:95]
	s_waitcnt lgkmcnt(8)
	v_mfma_f32_32x32x16_bf16 v[64:79], v[222:225], v[192:195], v[64:79]
	v_mfma_f32_32x32x16_bf16 v[112:127], v[176:179], v[164:167], v[112:127]
	v_mfma_f32_32x32x16_bf16 v[96:111], v[184:187], v[164:167], v[96:111]
	v_mfma_f32_32x32x16_bf16 v[112:127], v[180:183], v[192:195], v[112:127]
	ds_read_b128 v[164:167], v204 offset:6144
	ds_read_b128 v[176:179], v204 offset:7168
	ds_read_b128 v[180:183], v204 offset:14336
	ds_read_b128 v[184:187], v204 offset:15360
	ds_read_b128 v[196:199], v204 offset:22528
	ds_read_b128 v[200:203], v204 offset:23552
	ds_read_b128 v[222:225], v204 offset:30720
	ds_read_b128 v[230:233], v204 offset:31744
	v_mfma_f32_32x32x16_bf16 v[96:111], v[188:191], v[192:195], v[96:111]
	v_cvt_pk_bf16_f32 v188, v16, v17
	v_cvt_pk_bf16_f32 v189, v18, v19
	v_cvt_pk_bf16_f32 v190, v20, v21
	v_cvt_pk_bf16_f32 v191, v22, v23
	s_waitcnt lgkmcnt(11)
	s_nop 0
	v_mfma_f32_32x32x16_bf16 v[80:95], v[172:175], v[188:191], v[80:95]
	v_cvt_pk_bf16_f32 v172, v24, v25
	v_cvt_pk_bf16_f32 v173, v26, v27
	v_cvt_pk_bf16_f32 v174, v28, v29
	v_cvt_pk_bf16_f32 v175, v30, v31
	s_waitcnt lgkmcnt(9)
	v_mfma_f32_32x32x16_bf16 v[64:79], v[234:237], v[188:191], v[64:79]
	v_mfma_f32_32x32x16_bf16 v[80:95], v[226:229], v[172:175], v[80:95]
	s_waitcnt lgkmcnt(8)
	v_mfma_f32_32x32x16_bf16 v[64:79], v[248:251], v[172:175], v[64:79]
	v_mfma_f32_32x32x16_bf16 v[112:127], v[152:155], v[188:191], v[112:127]
	v_mfma_f32_32x32x16_bf16 v[96:111], v[160:163], v[188:191], v[96:111]
	v_mfma_f32_32x32x16_bf16 v[112:127], v[156:159], v[172:175], v[112:127]
	ds_read_b128 v[152:155], v204 offset:49152
	ds_read_b128 v[156:159], v204 offset:50176
	ds_read_b128 v[160:163], v204 offset:51200
	ds_read_b128 v[188:191], v204 offset:52224
	ds_read_b128 v[192:195], v204 offset:53248
	ds_read_b128 v[226:229], v204 offset:54272
	ds_read_b128 v[234:237], v204 offset:55296
	ds_read_b128 v[248:251], v204 offset:56320
	v_mfma_f32_32x32x16_bf16 v[96:111], v[168:171], v[172:175], v[96:111]
	v_cvt_pk_bf16_f32 v168, v0, v1
	v_cvt_pk_bf16_f32 v169, v2, v3
	v_cvt_pk_bf16_f32 v170, v4, v5
	v_cvt_pk_bf16_f32 v171, v6, v7
	v_cvt_pk_bf16_f32 v172, v8, v9
	v_cvt_pk_bf16_f32 v173, v10, v11
	s_waitcnt lgkmcnt(13)
	v_mfma_f32_32x32x16_bf16 v[96:111], v[180:183], v[168:171], v[96:111]
	v_cvt_pk_bf16_f32 v174, v12, v13
	v_cvt_pk_bf16_f32 v175, v14, v15
	s_waitcnt lgkmcnt(11)
	v_mfma_f32_32x32x16_bf16 v[80:95], v[196:199], v[168:171], v[80:95]
	s_waitcnt lgkmcnt(9)
	v_mfma_f32_32x32x16_bf16 v[64:79], v[222:225], v[168:171], v[64:79]
	v_mfma_f32_32x32x16_bf16 v[96:111], v[184:187], v[172:175], v[96:111]
	v_mfma_f32_32x32x16_bf16 v[80:95], v[200:203], v[172:175], v[80:95]
	s_waitcnt lgkmcnt(8)
; #define MFMA32(a, b, c) __builtin_amdgcn_mfma_f32_32x32x16_bf16((a), (b), (c), 0, 0, 0)
; #define PACK8(v, base) pack8f((v)[(base) + 0], (v)[(base) + 1], (v)[(base) + 2], (v)[(base) + 3], (v)[(base) + 4], (v)[(base) + 5], (v)[(base) + 6], (v)[(base) + 7])
; #define SBAR() __builtin_amdgcn_sched_barrier(0)
; DI void gdn_scan(const Args& a, int l, int bh, LAS unsigned char* lds, const int tidx, const bool nostore) {
;     ...
;             bf16x8 Vb[4];
; #pragma unroll
;             for (int s2 = 0; s2 < 4; ++s2) Vb[s2] = PACK8(vn[s2 >> 1], (s2 & 1) * 8);
; #pragma unroll
;             for (int s2 = 0; s2 < 4; ++s2)
; #pragma unroll
;                 for (int mt = 0; mt < 2; ++mt) o[mt] = MFMA32(fa[mt * 4 + s2], Vb[s2], o[mt]);
;             SBAR();
; #pragma unroll
;             for (int e = 0; e < 8; ++e) fa[e] = LDF(32768 + 8192 + e * 1024);
;             SBAR();
; #pragma unroll
;             for (int t = 0; t < 4; ++t)
; #pragma unroll
;                 for (int r = 0; r < 16; ++r) S[t][r] *= eg;
; #pragma unroll
;             for (int s2 = 0; s2 < 4; ++s2)
; #pragma unroll
;                 for (int t = 0; t < 2; ++t) S[t] = MFMA32(fb[t * 4 + s2], Vb[s2], S[t]);
;             SBAR();
; #pragma unroll
;             for (int s2 = 0; s2 < 4; ++s2)
; #pragma unroll
;                 for (int t = 2; t < 4; ++t) S[t] = MFMA32(fa[(t - 2) * 4 + s2], Vb[s2], S[t]);
	v_mfma_f32_32x32x16_bf16 v[64:79], v[230:233], v[172:175], v[64:79]
	v_mfma_f32_32x32x16_bf16 v[112:127], v[164:167], v[168:171], v[112:127]
	ds_read_b128 v[164:167], v204 offset:32768
	ds_read_b128 v[168:171], v204 offset:33792
	ds_read_b128 v[180:183], v204 offset:34816
	ds_read_b128 v[184:187], v204 offset:35840
	ds_read_b128 v[196:199], v204 offset:36864
	ds_read_b128 v[200:203], v204 offset:37888
	ds_read_b128 v[222:225], v204 offset:38912
	ds_read_b128 v[230:233], v204 offset:39936
	v_mfma_f32_32x32x16_bf16 v[112:127], v[176:179], v[172:175], v[112:127]
	s_nop 11
	v_cvt_pk_bf16_f32 v112, v112, v113
	v_cvt_pk_bf16_f32 v113, v114, v115
	v_cvt_pk_bf16_f32 v114, v116, v117
	v_cvt_pk_bf16_f32 v115, v118, v119
	v_cvt_pk_bf16_f32 v116, v120, v121
	v_cvt_pk_bf16_f32 v117, v122, v123
	s_waitcnt lgkmcnt(14)
	v_mfma_f32_32x32x16_bf16 v[80:95], v[152:155], v[112:115], v[80:95]
	v_cvt_pk_bf16_f32 v118, v124, v125
	v_cvt_pk_bf16_f32 v119, v126, v127
	v_cvt_pk_bf16_f32 v96, v96, v97
	v_cvt_pk_bf16_f32 v97, v98, v99
	v_cvt_pk_bf16_f32 v98, v100, v101
	v_cvt_pk_bf16_f32 v99, v102, v103
	v_cvt_pk_bf16_f32 v100, v104, v105
	s_waitcnt lgkmcnt(11)
	v_mfma_f32_32x32x16_bf16 v[64:79], v[192:195], v[112:115], v[64:79]
	v_cvt_pk_bf16_f32 v101, v106, v107
	v_cvt_pk_bf16_f32 v102, v108, v109
	v_cvt_pk_bf16_f32 v103, v110, v111
	v_mfma_f32_32x32x16_bf16 v[80:95], v[156:159], v[116:119], v[80:95]
	s_waitcnt lgkmcnt(10)
	v_mfma_f32_32x32x16_bf16 v[64:79], v[226:229], v[116:119], v[64:79]
	v_mfma_f32_32x32x16_bf16 v[80:95], v[160:163], v[96:99], v[80:95]
	s_waitcnt lgkmcnt(9)
	v_mfma_f32_32x32x16_bf16 v[64:79], v[234:237], v[96:99], v[64:79]
	v_mfma_f32_32x32x16_bf16 v[80:95], v[188:191], v[100:103], v[80:95]
	s_waitcnt lgkmcnt(8)
	v_mfma_f32_32x32x16_bf16 v[64:79], v[248:251], v[100:103], v[64:79]
	ds_read_b128 v[104:107], v204 offset:40960
	ds_read_b128 v[108:111], v204 offset:41984
	ds_read_b128 v[120:123], v204 offset:43008
	ds_read_b128 v[124:127], v204 offset:44032
	ds_read_b128 v[152:155], v204 offset:45056
	ds_read_b128 v[156:159], v204 offset:46080
	ds_read_b128 v[160:163], v204 offset:47104
	ds_read_b128 v[172:175], v204 offset:48128
	s_nop 0
	v_mul_f32_e32 v62, v148, v62
	v_mul_f32_e32 v63, v148, v63
	v_mul_f32_e32 v60, v148, v60
	v_mul_f32_e32 v61, v148, v61
	v_mul_f32_e32 v58, v148, v58
	v_mul_f32_e32 v59, v148, v59
	v_mul_f32_e32 v56, v148, v56
	v_mul_f32_e32 v57, v148, v57
	v_mul_f32_e32 v54, v148, v54
	v_mul_f32_e32 v55, v148, v55
	v_mul_f32_e32 v52, v148, v52
	v_mul_f32_e32 v53, v148, v53
	v_mul_f32_e32 v50, v148, v50
	v_mul_f32_e32 v51, v148, v51
	v_mul_f32_e32 v48, v148, v48
	v_mul_f32_e32 v49, v148, v49
	v_mul_f32_e32 v46, v148, v46
	v_mul_f32_e32 v47, v148, v47
	v_mul_f32_e32 v44, v148, v44
	v_mul_f32_e32 v45, v148, v45
	v_mul_f32_e32 v42, v148, v42
	v_mul_f32_e32 v43, v148, v43
	v_mul_f32_e32 v40, v148, v40
	v_mul_f32_e32 v41, v148, v41
	v_mul_f32_e32 v38, v148, v38
	v_mul_f32_e32 v39, v148, v39
	v_mul_f32_e32 v36, v148, v36
	v_mul_f32_e32 v37, v148, v37
	v_mul_f32_e32 v34, v148, v34
	v_mul_f32_e32 v35, v148, v35
	v_mul_f32_e32 v32, v148, v32
	v_mul_f32_e32 v33, v148, v33
	s_waitcnt lgkmcnt(14)
	v_mfma_f32_32x32x16_bf16 v[48:63], v[164:167], v[112:115], v[48:63]
	v_mul_f32_e32 v30, v148, v30
	v_mul_f32_e32 v31, v148, v31
	v_mul_f32_e32 v28, v148, v28
	v_mul_f32_e32 v29, v148, v29
	v_mul_f32_e32 v26, v148, v26
	v_mul_f32_e32 v27, v148, v27
	v_mul_f32_e32 v24, v148, v24
	v_mul_f32_e32 v25, v148, v25
	v_mul_f32_e32 v22, v148, v22
	v_mul_f32_e32 v23, v148, v23
	v_mul_f32_e32 v20, v148, v20
	v_mul_f32_e32 v21, v148, v21
	v_mul_f32_e32 v18, v148, v18
	v_mul_f32_e32 v19, v148, v19
	s_waitcnt lgkmcnt(11)
	v_mfma_f32_32x32x16_bf16 v[32:47], v[196:199], v[112:115], v[32:47]
	v_mul_f32_e32 v16, v148, v16
	v_mul_f32_e32 v17, v148, v17
	v_mul_f32_e32 v14, v148, v14
	v_mul_f32_e32 v15, v148, v15
	v_mul_f32_e32 v12, v148, v12
	v_mul_f32_e32 v13, v148, v13
	v_mul_f32_e32 v10, v148, v10
	v_mul_f32_e32 v11, v148, v11
	v_mul_f32_e32 v8, v148, v8
	v_mul_f32_e32 v9, v148, v9
	v_mul_f32_e32 v6, v148, v6
	v_mul_f32_e32 v7, v148, v7
	v_mul_f32_e32 v4, v148, v4
	v_mul_f32_e32 v5, v148, v5
	v_mfma_f32_32x32x16_bf16 v[48:63], v[168:171], v[116:119], v[48:63]
	v_mul_f32_e32 v2, v148, v2
	v_mul_f32_e32 v3, v148, v3
	v_mul_f32_e32 v0, v148, v0
	v_mul_f32_e32 v1, v148, v1
	s_waitcnt lgkmcnt(10)
	v_mfma_f32_32x32x16_bf16 v[32:47], v[200:203], v[116:119], v[32:47]
	v_mfma_f32_32x32x16_bf16 v[48:63], v[180:183], v[96:99], v[48:63]
	s_waitcnt lgkmcnt(9)
	v_mfma_f32_32x32x16_bf16 v[32:47], v[222:225], v[96:99], v[32:47]
	v_mfma_f32_32x32x16_bf16 v[48:63], v[184:187], v[100:103], v[48:63]
	s_waitcnt lgkmcnt(8)
	v_mfma_f32_32x32x16_bf16 v[32:47], v[230:233], v[100:103], v[32:47]
	s_waitcnt lgkmcnt(7)
	v_mfma_f32_32x32x16_bf16 v[16:31], v[104:107], v[112:115], v[16:31]
	s_mulk_i32 s5, 0x4400
	v_cvt_pk_bf16_f32 v80, v80, v81
	v_cvt_pk_bf16_f32 v81, v82, v83
	v_cvt_pk_bf16_f32 v64, v64, v65
	v_cvt_pk_bf16_f32 v65, v66, v67
	s_add_i32 s4, s4, 1
	s_add_u32 s0, s0, 4
	s_waitcnt lgkmcnt(3)
	v_mfma_f32_32x32x16_bf16 v[0:15], v[152:155], v[112:115], v[0:15]
	s_addc_u32 s1, s1, 0
	v_lshl_add_u64 v[144:145], v[144:145], 0, s[10:11]
	v_lshl_add_u64 v[146:147], v[146:147], 0, s[10:11]
	s_cmp_eq_u32 s4, 63
	v_mfma_f32_32x32x16_bf16 v[16:31], v[108:111], v[116:119], v[16:31]
	s_waitcnt lgkmcnt(2)
	v_mfma_f32_32x32x16_bf16 v[0:15], v[156:159], v[116:119], v[0:15]
	v_mfma_f32_32x32x16_bf16 v[16:31], v[120:123], v[96:99], v[16:31]
	s_waitcnt lgkmcnt(1)
; #define LAS __attribute__((address_space(3)))
; DI unsigned pk2(float lo, float hi) { const f32x2_t v = {lo, hi}; return __builtin_bit_cast(unsigned, __builtin_convertvector(v, bf16x2_t)); }
; DI void gdn_scan(const Args& a, int l, int bh, LAS unsigned char* lds, const int tidx, const bool nostore) {
;     ...
;             for (int mt = 0; mt < 2; ++mt) {
; #pragma unroll
;                 for (int g8 = 0; g8 < 2; ++g8) { const u32x4 u = un[mt][g8];
;                     vn[mt][8 * g8] = bflo(u.x); vn[mt][8 * g8 + 1] = bfhi(u.x); vn[mt][8 * g8 + 2] = bflo(u.y); vn[mt][8 * g8 + 3] = bfhi(u.y);
;                     vn[mt][8 * g8 + 4] = bflo(u.z); vn[mt][8 * g8 + 5] = bfhi(u.z); vn[mt][8 * g8 + 6] = bflo(u.w); vn[mt][8 * g8 + 7] = bfhi(u.w); }
; #pragma unroll
;                 for (int r = 0; r < 16; ++r) o[mt][r] = 0.f; }
;             if (n < 63) {
; #pragma unroll
;                 for (int mt = 0; mt < 2; ++mt) { const u32x4* up = (const u32x4*)(urec + (size_t)(n + 1) * 16384) + ((size_t)((wave * 2 + mt) * 64 + lane)) * 2; un[mt][0] = up[0]; un[mt][1] = up[1]; }
;                 egn = egl[n + 1];
;             }
;             const LAS unsigned char* buf = lds + (n & 1) * REC_BYTES + lane * 16;
;             bf16x8 fa[8], fb[8];
;     ...
;             LOAD_WQ(fa, 0); SBAR(); LOAD_WQ(fb, 1); SBAR();
;             COMP_WQ(fa, 0); SBAR(); LOAD_WQ(fa, 2); SBAR();
;     ...
;             for (int s2 = 0; s2 < 4; ++s2)
; #pragma unroll
;                 for (int t = 0; t < 2; ++t) S[t] = MFMA32(fb[t * 4 + s2], Vb[s2], S[t]);
;             SBAR();
; #pragma unroll
;             for (int s2 = 0; s2 < 4; ++s2)
; #pragma unroll
;                 for (int t = 2; t < 4; ++t) S[t] = MFMA32(fa[(t - 2) * 4 + s2], Vb[s2], S[t]);
;     ...
;             LAS bf16_t* ost = (LAS bf16_t*)(lds + SCAN_OST + (n & 1) * OST_BYTES) + (4 * hf) * OST_PITCH + wave * 32 + (lane & 31);
; #pragma unroll
;             for (int mt = 0; mt < 2; ++mt)
; #pragma unroll
;                 for (int i = 0; i < 4; ++i) { const unsigned w0 = pk2(o[mt][4 * i], o[mt][4 * i + 1]), w1 = pk2(o[mt][4 * i + 2], o[mt][4 * i + 3]);
;                     LAS bf16_t* d = ost + (mt * 32 + 8 * i) * OST_PITCH;
;                     d[0] = (bf16_t)(w0 & 0xffffu); d[OST_PITCH] = (bf16_t)(w0 >> 16); d[2 * OST_PITCH] = (bf16_t)(w1 & 0xffffu); d[3 * OST_PITCH] = (bf16_t)(w1 >> 16); }
;             LDSBAR();
	v_mfma_f32_32x32x16_bf16 v[0:15], v[160:163], v[96:99], v[0:15]
	v_add_u32_e32 v96, s5, v149
	ds_write_b16 v96, v80
	ds_write_b16_d16_hi v96, v80 offset:272
	ds_write_b16 v96, v81 offset:544
	ds_write_b16_d16_hi v96, v81 offset:816
	v_cvt_pk_bf16_f32 v80, v84, v85
	v_cvt_pk_bf16_f32 v81, v86, v87
	ds_write_b16 v96, v80 offset:2176
	ds_write_b16_d16_hi v96, v80 offset:2448
	ds_write_b16 v96, v81 offset:2720
	ds_write_b16_d16_hi v96, v81 offset:2992
	v_cvt_pk_bf16_f32 v80, v88, v89
	v_cvt_pk_bf16_f32 v81, v90, v91
	v_mfma_f32_32x32x16_bf16 v[16:31], v[124:127], v[100:103], v[16:31]
	ds_write_b16 v96, v80 offset:4352
	ds_write_b16_d16_hi v96, v80 offset:4624
	ds_write_b16 v96, v81 offset:4896
	ds_write_b16_d16_hi v96, v81 offset:5168
	v_cvt_pk_bf16_f32 v80, v92, v93
	v_cvt_pk_bf16_f32 v81, v94, v95
	ds_write_b16 v96, v80 offset:6528
	ds_write_b16_d16_hi v96, v80 offset:6800
	ds_write_b16 v96, v81 offset:7072
	ds_write_b16_d16_hi v96, v81 offset:7344
	ds_write_b16 v96, v64 offset:8704
	ds_write_b16_d16_hi v96, v64 offset:8976
	ds_write_b16 v96, v65 offset:9248
	ds_write_b16_d16_hi v96, v65 offset:9520
	v_cvt_pk_bf16_f32 v64, v68, v69
	v_cvt_pk_bf16_f32 v65, v70, v71
	s_waitcnt lgkmcnt(14)
	v_mfma_f32_32x32x16_bf16 v[0:15], v[172:175], v[100:103], v[0:15]
	ds_write_b16 v96, v64 offset:10880
	ds_write_b16_d16_hi v96, v64 offset:11152
	ds_write_b16 v96, v65 offset:11424
	ds_write_b16_d16_hi v96, v65 offset:11696
	v_cvt_pk_bf16_f32 v64, v72, v73
	v_cvt_pk_bf16_f32 v65, v74, v75
	ds_write_b16 v96, v64 offset:13056
	ds_write_b16_d16_hi v96, v64 offset:13328
	ds_write_b16 v96, v65 offset:13600
	ds_write_b16_d16_hi v96, v65 offset:13872
	v_cvt_pk_bf16_f32 v64, v76, v77
	v_cvt_pk_bf16_f32 v65, v78, v79
	ds_write_b16 v96, v64 offset:15232
	ds_write_b16_d16_hi v96, v64 offset:15504
	ds_write_b16 v96, v65 offset:15776
	ds_write_b16_d16_hi v96, v65 offset:16048
	s_waitcnt lgkmcnt(0)
	s_barrier
	s_cbranch_scc0 .LBB0_380
	s_waitcnt vmcnt(5)
	v_add_u32_e32 v96, 0x10000, v150
	v_lshlrev_b32_e32 v80, 16, v132
	v_and_b32_e32 v81, 0xffff0000, v132
	v_lshlrev_b32_e32 v82, 16, v133
	v_and_b32_e32 v83, 0xffff0000, v133
	v_lshlrev_b32_e32 v84, 16, v134
	v_and_b32_e32 v85, 0xffff0000, v134
	v_lshlrev_b32_e32 v86, 16, v135
	v_and_b32_e32 v87, 0xffff0000, v135
	v_lshlrev_b32_e32 v88, 16, v128
	v_and_b32_e32 v89, 0xffff0000, v128
	v_lshlrev_b32_e32 v90, 16, v129
	v_and_b32_e32 v91, 0xffff0000, v129
	v_lshlrev_b32_e32 v92, 16, v130
	v_and_b32_e32 v93, 0xffff0000, v130
	v_lshlrev_b32_e32 v94, 16, v131
	v_and_b32_e32 v95, 0xffff0000, v131
	ds_read_b128 v[128:131], v150 offset:57344
	ds_read_b128 v[132:135], v96
	v_add_u32_e32 v96, 0x12000, v150
	v_add_u32_e32 v100, 0x14000, v150
	v_add_u32_e32 v104, 0x10400, v150
	v_and_b32_e32 v79, 0xffff0000, v139
	v_lshlrev_b32_e32 v64, 16, v140
	v_and_b32_e32 v65, 0xffff0000, v140
	v_lshlrev_b32_e32 v66, 16, v141
	v_and_b32_e32 v67, 0xffff0000, v141
	v_lshlrev_b32_e32 v68, 16, v142
	v_and_b32_e32 v69, 0xffff0000, v142
	v_lshlrev_b32_e32 v70, 16, v143
	v_and_b32_e32 v71, 0xffff0000, v143
	v_lshlrev_b32_e32 v72, 16, v136
	v_and_b32_e32 v73, 0xffff0000, v136
	v_lshlrev_b32_e32 v74, 16, v137
	v_and_b32_e32 v75, 0xffff0000, v137
	v_lshlrev_b32_e32 v76, 16, v138
	v_and_b32_e32 v77, 0xffff0000, v138
	v_lshlrev_b32_e32 v78, 16, v139
	ds_read_b128 v[96:99], v96
	ds_read_b128 v[100:103], v100
	ds_read_b128 v[136:139], v150 offset:58368
	ds_read_b128 v[140:143], v104
	v_add_u32_e32 v104, 0x12400, v150
	ds_read_b128 v[144:147], v104
	v_add_u32_e32 v104, 0x14400, v150
	ds_read_b128 v[152:155], v104
	v_add_u32_e32 v104, 0x10800, v150
	v_add_u32_e32 v105, 0x12800, v150
	ds_read_b128 v[156:159], v104
	ds_read_b128 v[160:163], v105
	v_add_u32_e32 v104, 0x14800, v150
	ds_read_b128 v[164:167], v150 offset:59392
	ds_read_b128 v[168:171], v150 offset:60416
	v_add_u32_e32 v105, 0x10c00, v150
	ds_read_b128 v[172:175], v104
	ds_read_b128 v[176:179], v105
	v_add_u32_e32 v104, 0x12c00, v150
	v_add_u32_e32 v105, 0x14c00, v150
	ds_read_b128 v[180:183], v104
	ds_read_b128 v[184:187], v105
	v_cvt_pk_bf16_f32 v48, v48, v49
	v_cvt_pk_bf16_f32 v49, v50, v51
	v_cvt_pk_bf16_f32 v50, v52, v53
	v_cvt_pk_bf16_f32 v51, v54, v55
	v_cvt_pk_bf16_f32 v52, v56, v57
	v_cvt_pk_bf16_f32 v53, v58, v59
	s_waitcnt lgkmcnt(13)
	v_mfma_f32_32x32x16_bf16 v[112:127], v[96:99], v[48:51], 0
	v_cvt_pk_bf16_f32 v54, v60, v61
	v_cvt_pk_bf16_f32 v55, v62, v63
	s_waitcnt lgkmcnt(12)
	v_mfma_f32_32x32x16_bf16 v[96:111], v[100:103], v[48:51], 0
	s_waitcnt lgkmcnt(9)
	v_mfma_f32_32x32x16_bf16 v[112:127], v[144:147], v[52:55], v[112:127]
	s_waitcnt lgkmcnt(8)
	v_mfma_f32_32x32x16_bf16 v[96:111], v[152:155], v[52:55], v[96:111]
	v_mfma_f32_32x32x16_bf16 v[80:95], v[128:131], v[48:51], v[80:95]
	v_add_u32_e32 v56, 0x13000, v150
	v_add_u32_e32 v144, 0x13400, v150
	v_add_u32_e32 v148, 0x15400, v150
	v_mfma_f32_32x32x16_bf16 v[64:79], v[132:135], v[48:51], v[64:79]
	v_add_u32_e32 v48, 0x11000, v150
	v_add_u32_e32 v132, 0x15000, v150
	ds_read_b128 v[48:51], v48
	ds_read_b128 v[56:59], v56
	ds_read_b128 v[60:63], v150 offset:61440
	ds_read_b128 v[128:131], v150 offset:62464
	v_mfma_f32_32x32x16_bf16 v[80:95], v[136:139], v[52:55], v[80:95]
	v_add_u32_e32 v136, 0x11400, v150
	ds_read_b128 v[132:135], v132
	ds_read_b128 v[136:139], v136
	ds_read_b128 v[144:147], v144
	ds_read_b128 v[152:155], v148
	v_mfma_f32_32x32x16_bf16 v[64:79], v[140:143], v[52:55], v[64:79]
	v_cvt_pk_bf16_f32 v32, v32, v33
	v_cvt_pk_bf16_f32 v33, v34, v35
	v_cvt_pk_bf16_f32 v34, v36, v37
	v_cvt_pk_bf16_f32 v35, v38, v39
	v_cvt_pk_bf16_f32 v36, v40, v41
	v_cvt_pk_bf16_f32 v37, v42, v43
	s_waitcnt lgkmcnt(14)
; #define LAS __attribute__((address_space(3)))
; #define MFMA32(a, b, c) __builtin_amdgcn_mfma_f32_32x32x16_bf16((a), (b), (c), 0, 0, 0)
; DI void gdn_scan(const Args& a, int l, int bh, LAS unsigned char* lds, const int tidx, const bool nostore) {
;     ...
;             LOAD_WQ(fa, 0); SBAR(); LOAD_WQ(fb, 1); SBAR();
;             COMP_WQ(fa, 0); SBAR(); LOAD_WQ(fa, 2); SBAR();
;             COMP_WQ(fb, 1); SBAR(); LOAD_WQ(fb, 3); SBAR();
;             COMP_WQ(fa, 2); SBAR();
; #pragma unroll
;             for (int e = 0; e < 8; ++e) fa[e] = LDF(49152 + e * 1024);
;             SBAR();
;             COMP_WQ(fb, 3); SBAR();
; #pragma unroll
;             for (int e = 0; e < 8; ++e) fb[e] = LDF(32768 + e * 1024);
;             SBAR();
;             bf16x8 Vb[4];
; #pragma unroll
;             for (int s2 = 0; s2 < 4; ++s2) Vb[s2] = PACK8(vn[s2 >> 1], (s2 & 1) * 8);
; #pragma unroll
;             for (int s2 = 0; s2 < 4; ++s2)
; #pragma unroll
;                 for (int mt = 0; mt < 2; ++mt) o[mt] = MFMA32(fa[mt * 4 + s2], Vb[s2], o[mt]);
;             SBAR();
; #pragma unroll
;             for (int e = 0; e < 8; ++e) fa[e] = LDF(32768 + 8192 + e * 1024);
;             SBAR();
; #pragma unroll
;             for (int t = 0; t < 4; ++t)
; #pragma unroll
;                 for (int r = 0; r < 16; ++r) S[t][r] *= eg;
; #pragma unroll
;             for (int s2 = 0; s2 < 4; ++s2)
; #pragma unroll
;                 for (int t = 0; t < 2; ++t) S[t] = MFMA32(fb[t * 4 + s2], Vb[s2], S[t]);
;             SBAR();
; #pragma unroll
;             for (int s2 = 0; s2 < 4; ++s2)
; #pragma unroll
;                 for (int t = 2; t < 4; ++t) S[t] = MFMA32(fa[(t - 2) * 4 + s2], Vb[s2], S[t]);
;     ...
;             LAS bf16_t* ost = (LAS bf16_t*)(lds + SCAN_OST + (n & 1) * OST_BYTES) + (4 * hf) * OST_PITCH + wave * 32 + (lane & 31);
; #pragma unroll
;             for (int mt = 0; mt < 2; ++mt)
; #pragma unroll
;                 for (int i = 0; i < 4; ++i) { const unsigned w0 = pk2(o[mt][4 * i], o[mt][4 * i + 1]), w1 = pk2(o[mt][4 * i + 2], o[mt][4 * i + 3]);
;                     LAS bf16_t* d = ost + (mt * 32 + 8 * i) * OST_PITCH;
;                     d[0] = (bf16_t)(w0 & 0xffffu); d[OST_PITCH] = (bf16_t)(w0 >> 16); d[2 * OST_PITCH] = (bf16_t)(w1 & 0xffffu); d[3 * OST_PITCH] = (bf16_t)(w1 >> 16); }
;             LDSBAR();
;         }
;         __builtin_amdgcn_s_setprio(0);
	v_mfma_f32_32x32x16_bf16 v[112:127], v[160:163], v[32:35], v[112:127]
	v_cvt_pk_bf16_f32 v38, v44, v45
	v_cvt_pk_bf16_f32 v39, v46, v47
	s_waitcnt lgkmcnt(11)
	v_mfma_f32_32x32x16_bf16 v[96:111], v[172:175], v[32:35], v[96:111]
	s_waitcnt lgkmcnt(9)
	v_mfma_f32_32x32x16_bf16 v[112:127], v[180:183], v[36:39], v[112:127]
	s_waitcnt lgkmcnt(8)
	v_mfma_f32_32x32x16_bf16 v[96:111], v[184:187], v[36:39], v[96:111]
	v_mfma_f32_32x32x16_bf16 v[80:95], v[164:167], v[32:35], v[80:95]
	v_add_u32_e32 v40, 0x13800, v150
	v_add_u32_e32 v140, 0x15800, v150
	v_add_u32_e32 v148, 0x11c00, v150
	v_add_u32_e32 v151, 0x15c00, v150
	v_mfma_f32_32x32x16_bf16 v[64:79], v[156:159], v[32:35], v[64:79]
	v_add_u32_e32 v32, 0x11800, v150
	ds_read_b128 v[32:35], v32
	ds_read_b128 v[40:43], v40
	ds_read_b128 v[44:47], v150 offset:63488
	ds_read_b128 v[52:55], v150 offset:64512
	ds_read_b128 v[140:143], v140
	ds_read_b128 v[156:159], v148
	v_add_u32_e32 v148, 0x13c00, v150
	ds_read_b128 v[160:163], v148
	ds_read_b128 v[164:167], v151
	v_mfma_f32_32x32x16_bf16 v[80:95], v[168:171], v[36:39], v[80:95]
	v_mfma_f32_32x32x16_bf16 v[64:79], v[176:179], v[36:39], v[64:79]
	v_cvt_pk_bf16_f32 v16, v16, v17
	v_cvt_pk_bf16_f32 v17, v18, v19
	v_cvt_pk_bf16_f32 v18, v20, v21
	v_cvt_pk_bf16_f32 v19, v22, v23
	v_cvt_pk_bf16_f32 v20, v24, v25
	v_cvt_pk_bf16_f32 v21, v26, v27
	s_waitcnt lgkmcnt(14)
	v_mfma_f32_32x32x16_bf16 v[112:127], v[56:59], v[16:19], v[112:127]
	v_cvt_pk_bf16_f32 v22, v28, v29
	v_cvt_pk_bf16_f32 v23, v30, v31
	s_waitcnt lgkmcnt(11)
	v_mfma_f32_32x32x16_bf16 v[96:111], v[132:135], v[16:19], v[96:111]
	s_waitcnt lgkmcnt(9)
	v_mfma_f32_32x32x16_bf16 v[112:127], v[144:147], v[20:23], v[112:127]
	s_waitcnt lgkmcnt(8)
	v_mfma_f32_32x32x16_bf16 v[96:111], v[152:155], v[20:23], v[96:111]
	v_mfma_f32_32x32x16_bf16 v[80:95], v[60:63], v[16:19], v[80:95]
	v_add_u32_e32 v24, 0x1a000, v150
	v_add_u32_e32 v25, 0x1a400, v150
	v_add_u32_e32 v28, 0x1a800, v150
	v_add_u32_e32 v36, 0x1ac00, v150
	v_add_u32_e32 v56, 0x1b400, v150
	v_add_u32_e32 v60, 0x1b800, v150
	v_mfma_f32_32x32x16_bf16 v[64:79], v[48:51], v[16:19], v[64:79]
	v_add_u32_e32 v48, 0x1b000, v150
	ds_read_b128 v[16:19], v24
	ds_read_b128 v[24:27], v25
	ds_read_b128 v[28:31], v28
	ds_read_b128 v[36:39], v36
	ds_read_b128 v[48:51], v48
	ds_read_b128 v[56:59], v56
	v_mfma_f32_32x32x16_bf16 v[80:95], v[128:131], v[20:23], v[80:95]
	v_add_u32_e32 v128, 0x1bc00, v150
	ds_read_b128 v[60:63], v60
	ds_read_b128 v[128:131], v128
	v_mfma_f32_32x32x16_bf16 v[64:79], v[136:139], v[20:23], v[64:79]
	v_cvt_pk_bf16_f32 v0, v0, v1
	v_cvt_pk_bf16_f32 v1, v2, v3
	v_cvt_pk_bf16_f32 v2, v4, v5
	v_cvt_pk_bf16_f32 v3, v6, v7
	v_cvt_pk_bf16_f32 v4, v8, v9
	v_cvt_pk_bf16_f32 v5, v10, v11
	s_waitcnt lgkmcnt(14)
	v_mfma_f32_32x32x16_bf16 v[64:79], v[32:35], v[0:3], v[64:79]
	v_cvt_pk_bf16_f32 v6, v12, v13
	v_cvt_pk_bf16_f32 v7, v14, v15
	v_mfma_f32_32x32x16_bf16 v[112:127], v[40:43], v[0:3], v[112:127]
	s_waitcnt lgkmcnt(11)
	v_mfma_f32_32x32x16_bf16 v[96:111], v[140:143], v[0:3], v[96:111]
	s_waitcnt lgkmcnt(10)
	v_mfma_f32_32x32x16_bf16 v[64:79], v[156:159], v[4:7], v[64:79]
	s_waitcnt lgkmcnt(9)
	v_mfma_f32_32x32x16_bf16 v[112:127], v[160:163], v[4:7], v[112:127]
	s_waitcnt lgkmcnt(8)
	v_mfma_f32_32x32x16_bf16 v[96:111], v[164:167], v[4:7], v[96:111]
	v_mfma_f32_32x32x16_bf16 v[80:95], v[44:47], v[0:3], v[80:95]
	v_mfma_f32_32x32x16_bf16 v[80:95], v[52:55], v[4:7], v[80:95]
	s_nop 11
	v_cvt_pk_bf16_f32 v0, v80, v81
	v_cvt_pk_bf16_f32 v1, v82, v83
	v_cvt_pk_bf16_f32 v2, v84, v85
	v_cvt_pk_bf16_f32 v3, v86, v87
	s_waitcnt lgkmcnt(7)
	s_nop 0
	v_mfma_f32_32x32x16_bf16 v[112:127], v[16:19], v[0:3], v[112:127]
	s_waitcnt lgkmcnt(3)
	v_mfma_f32_32x32x16_bf16 v[96:111], v[48:51], v[0:3], v[96:111]
	v_cvt_pk_bf16_f32 v0, v88, v89
	v_cvt_pk_bf16_f32 v1, v90, v91
	v_cvt_pk_bf16_f32 v2, v92, v93
	v_cvt_pk_bf16_f32 v3, v94, v95
	s_nop 1
	v_mfma_f32_32x32x16_bf16 v[112:127], v[24:27], v[0:3], v[112:127]
	s_waitcnt lgkmcnt(2)
	v_mfma_f32_32x32x16_bf16 v[96:111], v[56:59], v[0:3], v[96:111]
	v_cvt_pk_bf16_f32 v0, v64, v65
	v_cvt_pk_bf16_f32 v1, v66, v67
	v_cvt_pk_bf16_f32 v2, v68, v69
	v_cvt_pk_bf16_f32 v3, v70, v71
	s_nop 1
	v_mfma_f32_32x32x16_bf16 v[112:127], v[28:31], v[0:3], v[112:127]
	s_waitcnt lgkmcnt(1)
	v_mfma_f32_32x32x16_bf16 v[96:111], v[60:63], v[0:3], v[96:111]
	v_cvt_pk_bf16_f32 v0, v72, v73
	v_cvt_pk_bf16_f32 v1, v74, v75
	v_cvt_pk_bf16_f32 v2, v76, v77
	v_cvt_pk_bf16_f32 v3, v78, v79
	s_nop 1
	v_mfma_f32_32x32x16_bf16 v[112:127], v[36:39], v[0:3], v[112:127]
	s_waitcnt lgkmcnt(0)
	v_mfma_f32_32x32x16_bf16 v[96:111], v[128:131], v[0:3], v[96:111]
	s_nop 9
	v_cvt_pk_bf16_f32 v0, v112, v113
	v_cvt_pk_bf16_f32 v1, v114, v115
	ds_write_b16 v149, v0 offset:17408
	ds_write_b16_d16_hi v149, v0 offset:17680
	ds_write_b16 v149, v1 offset:17952
	ds_write_b16_d16_hi v149, v1 offset:18224
	v_cvt_pk_bf16_f32 v0, v116, v117
	v_cvt_pk_bf16_f32 v1, v118, v119
	ds_write_b16 v149, v0 offset:19584
	ds_write_b16_d16_hi v149, v0 offset:19856
	ds_write_b16 v149, v1 offset:20128
	ds_write_b16_d16_hi v149, v1 offset:20400
	v_cvt_pk_bf16_f32 v0, v120, v121
	v_cvt_pk_bf16_f32 v1, v122, v123
	ds_write_b16 v149, v0 offset:21760
	ds_write_b16_d16_hi v149, v0 offset:22032
	ds_write_b16 v149, v1 offset:22304
	ds_write_b16_d16_hi v149, v1 offset:22576
	v_cvt_pk_bf16_f32 v0, v124, v125
	v_cvt_pk_bf16_f32 v1, v126, v127
	ds_write_b16 v149, v0 offset:23936
	ds_write_b16_d16_hi v149, v0 offset:24208
	ds_write_b16 v149, v1 offset:24480
	ds_write_b16_d16_hi v149, v1 offset:24752
	v_cvt_pk_bf16_f32 v0, v96, v97
	v_cvt_pk_bf16_f32 v1, v98, v99
	ds_write_b16 v149, v0 offset:26112
	ds_write_b16_d16_hi v149, v0 offset:26384
	ds_write_b16 v149, v1 offset:26656
	ds_write_b16_d16_hi v149, v1 offset:26928
	v_cvt_pk_bf16_f32 v0, v100, v101
	v_cvt_pk_bf16_f32 v1, v102, v103
	ds_write_b16 v149, v0 offset:28288
	ds_write_b16_d16_hi v149, v0 offset:28560
	ds_write_b16 v149, v1 offset:28832
	ds_write_b16_d16_hi v149, v1 offset:29104
	v_cvt_pk_bf16_f32 v0, v104, v105
	v_cvt_pk_bf16_f32 v1, v106, v107
	ds_write_b16 v149, v0 offset:30464
	ds_write_b16_d16_hi v149, v0 offset:30736
	ds_write_b16 v149, v1 offset:31008
	ds_write_b16_d16_hi v149, v1 offset:31280
	v_cvt_pk_bf16_f32 v0, v108, v109
	v_cvt_pk_bf16_f32 v1, v110, v111
	ds_write_b16 v149, v0 offset:32640
	ds_write_b16_d16_hi v149, v0 offset:32912
	ds_write_b16 v149, v1 offset:33184
	ds_write_b16_d16_hi v149, v1 offset:33456
	s_waitcnt lgkmcnt(0)
	s_barrier
	s_setprio 0
	v_mov_b64_e32 v[250:251], v[206:207]
	s_waitcnt vmcnt(0)
	v_mov_b64_e32 v[210:211], 0x800
	v_mov_b64_e32 v[212:213], 0x7ff
	v_mov_b32_e32 v214, 0x3f317218
	v_mov_b64_e32 v[216:217], 0x700
	v_mov_b64_e32 v[218:219], 0x6ff
	v_mov_b32_e32 v240, 0x358637bd
	v_mov_b32_e32 v241, 1
	v_mov_b32_e32 v242, 0x41b17218
	v_mov_b32_e32 v243, 0x3600000
